# combine loop: next-token prefetch no longer waited with vmcnt(0); IN[1] conversion also moved to the idle small-GEMM workgroups of layer 0 (3-level kind masks)
# baseline (speedup 1.0000x reference)
; __device__ __forceinline__ int bid_fresh() { int t = blockIdx.x; asm volatile("" : "+s"(t)); return t; }
; __device__ __forceinline__ void phase0(PP p, unsigned char* shm) {
;     ...
;     for (int it = bid_fresh(); it < DEPTH * C_LAYER; it += gridDim.x) {
;         const int l = it / C_LAYER; int r = it % C_LAYER;
;         if (r < C_IN) { tconv_tile_w(p->in[5] + (size_t)l * D * INW, INW, r / 14, r % 14, (bf16_t*)(ws + WS_WIN) + (size_t)l * INW * D, D, tile, p->in[4] + (size_t)l * D); continue; } r -= C_IN;
;         if (r < C_OUT) { tconv_tile_w(p->in[23] + (size_t)l * D * D, D, r / 8, r % 8, (bf16_t*)(ws + WS_WOUT) + (size_t)l * D * D, D, tile, p->in[22] + (size_t)l * D); continue; } r -= C_OUT;
;         if (r < C_XQ) { tconv_tile_w(p->in[25] + (size_t)l * D * 512, 512, r / 2, r % 2, (bf16_t*)(ws + WS_WXQ) + (size_t)l * 512 * D, D, tile, p->in[24] + (size_t)l * D); continue; } r -= C_XQ;
;         if (r < C_XQ) { tconv_tile_w(p->in[26] + (size_t)l * D * 512, 512, r / 2, r % 2, (bf16_t*)(ws + WS_WKV) + (size_t)(l * 1024) * D, D, tile); continue; } r -= C_XQ;
;         if (r < C_XQ) { tconv_tile_w(p->in[27] + (size_t)l * D * 512, 512, r / 2, r % 2, (bf16_t*)(ws + WS_WKV) + (size_t)(l * 1024 + 512) * D, D, tile); continue; } r -= C_XQ;
;         if (r < C_XO) { tconv_tile_w(p->in[28] + (size_t)l * 512 * D, D, r / 8, r % 8, (bf16_t*)(ws + WS_WXO) + (size_t)l * D * 512, 512, tile); continue; } r -= C_XO;
;         if (r < C_UP) { tconv_tile_w(p->in[30] + (size_t)l * D * DFF, DFF, r / 32, r % 32, (bf16_t*)(ws + WS_WUP) + (size_t)l * DFF * D, D, tile, p->in[29] + (size_t)l * D); continue; } r -= C_UP;
;         if (r < C_DN) { if (l == 0) tconv_tile_w(p->in[31] + (size_t)l * DFF * D, D, r / 8, r % 8, (bf16_t*)(ws + WS_WDN) + (size_t)l * D * DFF, DFF, tile); continue; } r -= C_DN;
.LBB0_17:
	s_mov_b64 s[14:15], s[0:1]
	s_load_dwordx2 s[12:13], s[14:15], 0x110
	v_writelane_b32 v254, s26, 2
	s_cmpk_gt_i32 s26, 0x2fbf
	s_cbranch_scc1 .LBB0_71
	s_mov_b32 s27, 0
	s_mov_b32 s28, 0
	s_mov_b32 s29, s26
	s_mov_b32 s63, s66
	s_mov_b32 s64, 0
	s_mov_b32 s65, 4
	s_mov_b32 s84, 0x1763ff
	s_mov_b32 s85, 0xbfe
	v_writelane_b32 v255, 0, 62

; __device__ __forceinline__ int bid_fresh() { int t = blockIdx.x; asm volatile("" : "+s"(t)); return t; }
; __device__ __forceinline__ void phase0(PP p, unsigned char* shm) {
;     ...
;     for (int it = bid_fresh(); it < DEPTH * C_LAYER; it += gridDim.x) {
;         const int l = it / C_LAYER; int r = it % C_LAYER;
;         if (r < C_IN) { tconv_tile_w(p->in[5] + (size_t)l * D * INW, INW, r / 14, r % 14, (bf16_t*)(ws + WS_WIN) + (size_t)l * INW * D, D, tile, p->in[4] + (size_t)l * D); continue; } r -= C_IN;
;         if (r < C_OUT) { tconv_tile_w(p->in[23] + (size_t)l * D * D, D, r / 8, r % 8, (bf16_t*)(ws + WS_WOUT) + (size_t)l * D * D, D, tile, p->in[22] + (size_t)l * D); continue; } r -= C_OUT;
;         if (r < C_XQ) { tconv_tile_w(p->in[25] + (size_t)l * D * 512, 512, r / 2, r % 2, (bf16_t*)(ws + WS_WXQ) + (size_t)l * 512 * D, D, tile, p->in[24] + (size_t)l * D); continue; } r -= C_XQ;
;         if (r < C_XQ) { tconv_tile_w(p->in[26] + (size_t)l * D * 512, 512, r / 2, r % 2, (bf16_t*)(ws + WS_WKV) + (size_t)(l * 1024) * D, D, tile); continue; } r -= C_XQ;
;         if (r < C_XQ) { tconv_tile_w(p->in[27] + (size_t)l * D * 512, 512, r / 2, r % 2, (bf16_t*)(ws + WS_WKV) + (size_t)(l * 1024 + 512) * D, D, tile); continue; } r -= C_XQ;
;         if (r < C_XO) { tconv_tile_w(p->in[28] + (size_t)l * 512 * D, D, r / 8, r % 8, (bf16_t*)(ws + WS_WXO) + (size_t)l * D * 512, 512, tile); continue; } r -= C_XO;
;         if (r < C_UP) { tconv_tile_w(p->in[30] + (size_t)l * D * DFF, DFF, r / 32, r % 32, (bf16_t*)(ws + WS_WUP) + (size_t)l * DFF * D, D, tile, p->in[29] + (size_t)l * D); continue; } r -= C_UP;
;         if (r < C_DN) { if (l == 0) tconv_tile_w(p->in[31] + (size_t)l * DFF * D, D, r / 8, r % 8, (bf16_t*)(ws + WS_WDN) + (size_t)l * D * DFF, DFF, tile); continue; } r -= C_DN;
;         bf16_t* wsm = (bf16_t*)(ws + WS_WSM) + (size_t)l * 1536 * 512;
;         if (r < C_GLU) { tconv_tile_w(p->in[14] + (size_t)l * 512 * 512, 512, r / 2, r % 2, wsm, 512, tile); continue; } r -= C_GLU;
;         if (r < C_POOL) { const int gi = r >> 2, q = r & 3; tconv_tile(p->in[15] + (size_t)(l * 4 + gi) * 128 * 128, 128, q >> 1, q & 1, wsm + (size_t)(512 + gi * 128) * 512 + gi * 128, 512, tile); continue; } r -= C_POOL;
;         tconv_tile_w(p->in[21] + (size_t)l * 512 * 512, 512, r / 2, r % 2, wsm + (size_t)1024 * 512, 512, tile);
;     }
.Ltc_mmid_12:
	s_bfe_u32 s2, s85, 0x3000a
	s_cmp_lt_u32 s27, s2
	s_cbranch_scc0 .Ltc_mhi_10
	s_and_b32 s2, s85, 0x3ff
	s_branch .Ltc_mdone_11

; __device__ __forceinline__ int bid_fresh() { int t = blockIdx.x; asm volatile("" : "+s"(t)); return t; }
; __global__ void __launch_bounds__(512, 2) hymba_fwd(Params p_unused) {
;     ...
;           { const int G = (int)gridDim.x, c = (int)bid_fresh(), nfull = 448 % G, nidle = (nfull == 0) ? 0 : G - nfull;
;             if (nidle > 0 && c >= nfull) { for (int r = c - nfull; r < 1024; r += nidle)
;                 tconv_tile_w(p->in[31] + (size_t)l * DFF * D, D, r / 8, r % 8, (bf16_t*)(ws + WS_WDN) + (size_t)l * D * DFF, DFF, (float*)shm); }
;             else if (nidle == 0) { for (int r = c; r < 1024; r += G) tconv_tile_w(p->in[31] + (size_t)l * DFF * D, D, r / 8, r % 8, (bf16_t*)(ws + WS_WDN) + (size_t)l * D * DFF, DFF, (float*)shm); } } }
.LBB0_286:
	s_mov_b32 s12, s30
	v_readlane_b32 s2, v254, 52
	s_cmp_lt_i32 s12, s2
	v_readlane_b32 s16, v254, 49
	s_cselect_b64 s[2:3], -1, 0
	v_readlane_b32 s17, v254, 50
	s_or_b64 s[16:17], s[2:3], s[16:17]
	s_mov_b64 s[2:3], -1
	s_and_b64 vcc, exec, s[16:17]
	s_cbranch_vccnz .LBB0_291
	v_readlane_b32 s2, v254, 52
	s_sub_i32 s2, s12, s2
	s_cmpk_gt_i32 s2, 0x3ff
	v_readlane_b32 s24, v255, 17
	v_readlane_b32 s25, v254, 54
	s_movk_i32 s34, 0x404
	s_cbranch_scc1 .LBB0_290
	s_waitcnt lgkmcnt(0)
	v_writelane_b32 v124, s2, 0
	v_writelane_b32 v124, s3, 1
	v_writelane_b32 v124, s4, 2
	v_writelane_b32 v124, s5, 3
	v_writelane_b32 v124, s6, 4
	v_writelane_b32 v124, s7, 5
	v_writelane_b32 v124, s12, 6
	v_writelane_b32 v124, s13, 7
	v_writelane_b32 v124, s14, 8
	v_writelane_b32 v124, s15, 9
	v_writelane_b32 v124, s27, 10
	v_writelane_b32 v124, s28, 11
	v_writelane_b32 v124, s29, 12
	v_writelane_b32 v124, s30, 13
	v_writelane_b32 v124, s31, 14
	v_writelane_b32 v124, s33, 15
	v_writelane_b32 v124, s34, 16
	v_writelane_b32 v124, s35, 17
	v_writelane_b32 v124, s36, 18
	v_writelane_b32 v124, s37, 19
	v_writelane_b32 v124, s38, 20
	v_writelane_b32 v124, s39, 21
	v_writelane_b32 v124, s40, 22
	v_writelane_b32 v124, s41, 23
	v_writelane_b32 v124, s42, 24
	v_writelane_b32 v124, s43, 25
	v_writelane_b32 v124, s44, 26
	v_writelane_b32 v124, s45, 27
	v_writelane_b32 v124, s46, 28
	v_writelane_b32 v124, s47, 29
	v_writelane_b32 v124, s48, 30
	v_writelane_b32 v124, s49, 31
	v_writelane_b32 v124, s50, 32
	v_writelane_b32 v124, s51, 33
	v_writelane_b32 v124, s52, 34
	v_writelane_b32 v124, s53, 35
	v_writelane_b32 v124, s54, 36
	v_writelane_b32 v124, s55, 37
	v_writelane_b32 v124, s56, 38
	v_writelane_b32 v124, s57, 39
	v_writelane_b32 v124, s58, 40
	v_writelane_b32 v124, s59, 41
	v_writelane_b32 v124, s60, 42
	v_writelane_b32 v124, s61, 43
	v_writelane_b32 v124, s62, 44
	v_writelane_b32 v124, s63, 45
	v_writelane_b32 v124, s64, 46
	v_writelane_b32 v124, s65, 47
	v_writelane_b32 v124, s68, 48
	v_writelane_b32 v124, s69, 49
	v_writelane_b32 v124, s70, 50
	v_writelane_b32 v124, s71, 51
	v_writelane_b32 v124, s72, 52
	v_writelane_b32 v124, s73, 53
	v_writelane_b32 v124, s74, 54
	v_writelane_b32 v124, s75, 55
	v_writelane_b32 v124, s76, 56
	v_writelane_b32 v124, s77, 57
	v_writelane_b32 v124, s78, 58
	v_writelane_b32 v124, s79, 59
	v_writelane_b32 v124, s80, 60
	v_writelane_b32 v124, s81, 61
	v_writelane_b32 v124, s82, 62
	v_writelane_b32 v124, s83, 63
	v_writelane_b32 v125, s84, 0
	v_writelane_b32 v125, s85, 1
	s_mov_b32 s84, 0x89800
	s_mov_b32 s85, 0
	v_readlane_b32 s29, v254, 2
	v_readlane_b32 s3, v254, 52
	v_readlane_b32 s63, v255, 17
	v_readlane_b32 s27, v255, 20
	s_mov_b64 s[14:15], s[0:1]
	s_load_dwordx2 s[12:13], s[0:1], 0x110
	s_nop 3
	s_sub_u32 s29, s29, s3
	s_mov_b32 s64, s27
	s_add_u32 s65, s27, 2
	s_min_u32 s65, s65, 4
	s_add_u32 s27, s27, 0
	s_mov_b32 s28, 9
	v_writelane_b32 v255, 1, 62
	s_branch .Ltc_entry
.Ltc_ret1:
	v_readlane_b32 s2, v124, 0
	v_readlane_b32 s3, v124, 1
	v_readlane_b32 s4, v124, 2
	v_readlane_b32 s5, v124, 3
	v_readlane_b32 s6, v124, 4
	v_readlane_b32 s7, v124, 5
	v_readlane_b32 s12, v124, 6
	v_readlane_b32 s13, v124, 7
	v_readlane_b32 s14, v124, 8
	v_readlane_b32 s15, v124, 9
	v_readlane_b32 s27, v124, 10
	v_readlane_b32 s28, v124, 11
	v_readlane_b32 s29, v124, 12
	v_readlane_b32 s30, v124, 13
	v_readlane_b32 s31, v124, 14
	v_readlane_b32 s33, v124, 15
	v_readlane_b32 s34, v124, 16
	v_readlane_b32 s35, v124, 17
	v_readlane_b32 s36, v124, 18
	v_readlane_b32 s37, v124, 19
	v_readlane_b32 s38, v124, 20
	v_readlane_b32 s39, v124, 21
	v_readlane_b32 s40, v124, 22
	v_readlane_b32 s41, v124, 23
	v_readlane_b32 s42, v124, 24
	v_readlane_b32 s43, v124, 25
	v_readlane_b32 s44, v124, 26
	v_readlane_b32 s45, v124, 27
	v_readlane_b32 s46, v124, 28
	v_readlane_b32 s47, v124, 29
	v_readlane_b32 s48, v124, 30
	v_readlane_b32 s49, v124, 31
	v_readlane_b32 s50, v124, 32
	v_readlane_b32 s51, v124, 33
	v_readlane_b32 s52, v124, 34
	v_readlane_b32 s53, v124, 35
	v_readlane_b32 s54, v124, 36
	v_readlane_b32 s55, v124, 37
	v_readlane_b32 s56, v124, 38
	v_readlane_b32 s57, v124, 39
	v_readlane_b32 s58, v124, 40
	v_readlane_b32 s59, v124, 41
	v_readlane_b32 s60, v124, 42
	v_readlane_b32 s61, v124, 43
	v_readlane_b32 s62, v124, 44
	v_readlane_b32 s63, v124, 45
	v_readlane_b32 s64, v124, 46
	v_readlane_b32 s65, v124, 47
	v_readlane_b32 s68, v124, 48
	v_readlane_b32 s69, v124, 49
	v_readlane_b32 s70, v124, 50
	v_readlane_b32 s71, v124, 51
	v_readlane_b32 s72, v124, 52
	v_readlane_b32 s73, v124, 53
	v_readlane_b32 s74, v124, 54
	v_readlane_b32 s75, v124, 55
	v_readlane_b32 s76, v124, 56
	v_readlane_b32 s77, v124, 57
	v_readlane_b32 s78, v124, 58
	v_readlane_b32 s79, v124, 59
	v_readlane_b32 s80, v124, 60
	v_readlane_b32 s81, v124, 61
	v_readlane_b32 s82, v124, 62
	v_readlane_b32 s83, v124, 63
	v_readlane_b32 s84, v125, 0
	v_readlane_b32 s85, v125, 1
	v_mov_b32_e32 v1, 0
	s_nop 3

; __device__ __forceinline__ unsigned pk2(float lo, float hi) { const hf32x2 v = {lo, hi}; return __builtin_bit_cast(unsigned, __builtin_convertvector(v, hbf16x2)); }
; __device__ __forceinline__ void phase_combine(PP p) {
;     ...
;     for (int t = gw; t < T; t += NGW) {
;         const bool more = (t + NGW) < T;
;         if (more) cb_load(nxt, ob, lse, t + NGW, lane);
;         const float lm = fmaxf(cur.ls[0], fmaxf(cur.ls[1], cur.ls[2]));
;         const float e0 = __expf(cur.ls[0] - lm), e1 = __expf(cur.ls[1] - lm), e2 = __expf(cur.ls[2] - lm), ei = 1.0f / (e0 + e1 + e2);
;         float o0[8], o1[8], o2[8], v[8];
;         unpack8(cur.ob[0], o0); unpack8(cur.ob[1], o1); unpack8(cur.ob[2], o2);
;         float sq = 0.f;
; #pragma unroll
;         for (int e = 0; e < 8; ++e) { v[e] = (e0 * o0[e] + e1 * o1[e] + e2 * o2[e]) * ei; sq += v[e] * v[e]; }
;         sq = wave_sum(sq);
;         u32x4 ov; ov.x = pk2(v[0], v[1]); ov.y = pk2(v[2], v[3]); ov.z = pk2(v[4], v[5]); ov.w = pk2(v[6], v[7]);
;         *(u32x4*)(y + (size_t)t * D + 1536 + lane * 8) = ov;
;         if (lane < 8) ssg[(size_t)t * 32 + 24 + lane] = (lane == 0) ? sq : 0.f;
;         if (more) cur = nxt;
;     }
.LBB0_720:
	s_or_b64 exec, exec, s[16:17]
	s_and_b64 s[16:17], exec, s[42:43]
	s_or_b64 s[2:3], s[16:17], s[2:3]
	v_readlane_b32 s16, v254, 63
	v_readlane_b32 s17, v255, 0
	s_waitcnt vmcnt(2) lgkmcnt(0)
	v_mov_b64_e32 v[2:3], v[14:15]
	v_mov_b64_e32 v[6:7], v[18:19]
	v_lshl_add_u64 v[28:29], v[28:29], 0, s[16:17]
	v_readlane_b32 s16, v255, 1
	v_readlane_b32 s17, v255, 2
	v_mov_b64_e32 v[10:11], v[22:23]
	v_mov_b32_e32 v45, v42
	v_lshl_add_u64 v[30:31], v[30:31], 0, s[16:17]
	v_readlane_b32 s16, v255, 3
	v_readlane_b32 s17, v255, 4
	v_mov_b64_e32 v[4:5], v[16:17]
	v_mov_b64_e32 v[8:9], v[20:21]
	v_lshl_add_u64 v[32:33], v[32:33], 0, s[16:17]
	v_readlane_b32 s16, v255, 7
	v_readlane_b32 s17, v255, 8
	v_mov_b64_e32 v[12:13], v[24:25]
	v_mov_b32_e32 v43, v0
	v_lshl_add_u64 v[34:35], v[34:35], 0, s[16:17]
	v_mov_b32_e32 v44, v41
	s_andn2_b64 exec, exec, s[2:3]
	s_cbranch_execz .LBB0_725

; __device__ __forceinline__ unsigned pk2(float lo, float hi) { const hf32x2 v = {lo, hi}; return __builtin_bit_cast(unsigned, __builtin_convertvector(v, hbf16x2)); }
; __device__ __forceinline__ void phase_combine(PP p) {
;     ...
;         const float lm = fmaxf(cur.ls[0], fmaxf(cur.ls[1], cur.ls[2]));
;         const float e0 = __expf(cur.ls[0] - lm), e1 = __expf(cur.ls[1] - lm), e2 = __expf(cur.ls[2] - lm), ei = 1.0f / (e0 + e1 + e2);
;         float o0[8], o1[8], o2[8], v[8];
;         unpack8(cur.ob[0], o0); unpack8(cur.ob[1], o1); unpack8(cur.ob[2], o2);
;         float sq = 0.f;
; #pragma unroll
;         for (int e = 0; e < 8; ++e) { v[e] = (e0 * o0[e] + e1 * o1[e] + e2 * o2[e]) * ei; sq += v[e] * v[e]; }
;         sq = wave_sum(sq);
;         u32x4 ov; ov.x = pk2(v[0], v[1]); ov.y = pk2(v[2], v[3]); ov.z = pk2(v[4], v[5]); ov.w = pk2(v[6], v[7]);
;         *(u32x4*)(y + (size_t)t * D + 1536 + lane * 8) = ov;
;         if (lane < 8) ssg[(size_t)t * 32 + 24 + lane] = (lane == 0) ? sq : 0.f;
;         if (more) cur = nxt;
.LBB0_723:
	s_or_b64 exec, exec, s[20:21]
	s_cmp_eq_u64 s[42:43], 0
	s_cbranch_scc1 .Lcb_relaxed
	s_waitcnt vmcnt(0)
	s_branch .Lcb_wdone
.Lcb_relaxed:
	s_waitcnt vmcnt(6)
.Lcb_wdone:
	v_max3_f32 v47, v43, v44, v45
	v_sub_f32_e32 v43, v43, v47
	v_mul_f32_e32 v43, 0x3fb8aa3b, v43
	v_exp_f32_e32 v46, v43
	v_sub_f32_e32 v43, v44, v47
	v_mul_f32_e32 v43, 0x3fb8aa3b, v43
	v_exp_f32_e32 v44, v43
	v_sub_f32_e32 v43, v45, v47
	v_mul_f32_e32 v43, 0x3fb8aa3b, v43
	v_exp_f32_e32 v48, v43
	v_add_f32_e32 v43, v46, v44
	v_lshlrev_b32_e32 v54, 16, v6
	v_and_b32_e32 v55, 0xffff0000, v6
	v_add_f32_e32 v43, v48, v43
	v_div_scale_f32 v45, s[16:17], v43, v43, 1.0
	v_rcp_f32_e32 v47, v45
	v_lshlrev_b32_e32 v52, 16, v2
	v_and_b32_e32 v53, 0xffff0000, v2
	v_lshlrev_b32_e32 v6, 16, v7
	v_fma_f32 v49, -v45, v47, 1.0
	v_fmac_f32_e32 v47, v49, v47
	v_div_scale_f32 v49, vcc, 1.0, v43, 1.0
	v_mul_f32_e32 v50, v49, v47
	v_fma_f32 v51, -v45, v50, v49
	v_fmac_f32_e32 v50, v51, v47
	v_fma_f32 v45, -v45, v50, v49
	v_div_fmas_f32 v45, v45, v47, v50
	v_pk_mul_f32 v[54:55], v[44:45], v[54:55] op_sel_hi:[0,1]
	v_and_b32_e32 v7, 0xffff0000, v7
	v_lshlrev_b32_e32 v56, 16, v10
	v_and_b32_e32 v57, 0xffff0000, v10
	v_pk_fma_f32 v[52:53], v[46:47], v[52:53], v[54:55] op_sel_hi:[0,1,1]
	v_lshlrev_b32_e32 v2, 16, v3
	v_and_b32_e32 v3, 0xffff0000, v3
	v_pk_mul_f32 v[6:7], v[44:45], v[6:7] op_sel_hi:[0,1]
	v_div_fixup_f32 v50, v45, v43, 1.0
	v_pk_fma_f32 v[52:53], v[48:49], v[56:57], v[52:53] op_sel_hi:[0,1,1]
	v_lshlrev_b32_e32 v10, 16, v11
	v_and_b32_e32 v11, 0xffff0000, v11
	v_pk_fma_f32 v[2:3], v[46:47], v[2:3], v[6:7] op_sel_hi:[0,1,1]
	v_lshlrev_b32_e32 v56, 16, v8
	v_and_b32_e32 v57, 0xffff0000, v8
	v_lshlrev_b32_e32 v8, 16, v9
	v_and_b32_e32 v9, 0xffff0000, v9
	v_pk_mul_f32 v[52:53], v[50:51], v[52:53] op_sel_hi:[0,1]
	v_pk_fma_f32 v[2:3], v[48:49], v[10:11], v[2:3] op_sel_hi:[0,1,1]
	v_lshlrev_b32_e32 v10, 16, v4
	v_and_b32_e32 v11, 0xffff0000, v4
	v_pk_mul_f32 v[56:57], v[44:45], v[56:57] op_sel_hi:[0,1]
	v_lshlrev_b32_e32 v4, 16, v5
	v_and_b32_e32 v5, 0xffff0000, v5
	v_pk_mul_f32 v[8:9], v[44:45], v[8:9] op_sel_hi:[0,1]
	v_pk_mul_f32 v[54:55], v[52:53], v[52:53]
	v_pk_mul_f32 v[6:7], v[50:51], v[2:3] op_sel_hi:[0,1]
	v_lshlrev_b32_e32 v58, 16, v12
	v_and_b32_e32 v59, 0xffff0000, v12
	v_pk_fma_f32 v[10:11], v[46:47], v[10:11], v[56:57] op_sel_hi:[0,1,1]
	v_lshlrev_b32_e32 v12, 16, v13
	v_and_b32_e32 v13, 0xffff0000, v13
	v_pk_fma_f32 v[4:5], v[46:47], v[4:5], v[8:9] op_sel_hi:[0,1,1]
	v_pk_mul_f32 v[2:3], v[6:7], v[6:7]
	v_pk_fma_f32 v[10:11], v[48:49], v[58:59], v[10:11] op_sel_hi:[0,1,1]
	v_pk_fma_f32 v[4:5], v[48:49], v[12:13], v[4:5] op_sel_hi:[0,1,1]
	v_add_f32_e32 v12, v54, v55
	v_pk_mul_f32 v[10:11], v[50:51], v[10:11] op_sel_hi:[0,1]
	v_add_f32_e32 v2, v2, v12
	v_pk_mul_f32 v[56:57], v[10:11], v[10:11]
	v_add_f32_e32 v2, v3, v2
	v_pk_mul_f32 v[8:9], v[50:51], v[4:5] op_sel_hi:[0,1]
	v_add_f32_e32 v2, v56, v2
	v_pk_mul_f32 v[4:5], v[8:9], v[8:9]
	v_add_f32_e32 v2, v57, v2
	v_add_f32_e32 v2, v4, v2
	v_add_f32_e32 v2, v5, v2
	ds_bpermute_b32 v3, v27, v2
	v_cvt_pk_bf16_f32 v4, v52, v53
	v_cvt_pk_bf16_f32 v5, v6, v7
	v_cvt_pk_bf16_f32 v6, v10, v11
	v_cvt_pk_bf16_f32 v7, v8, v9
	s_waitcnt lgkmcnt(0)
	v_add_f32_e32 v2, v2, v3
	ds_bpermute_b32 v3, v36, v2
	v_lshl_add_u64 v[8:9], s[12:13], 0, v[30:31]
	global_store_dwordx4 v[8:9], v[4:7], off
	s_waitcnt lgkmcnt(0)
	v_add_f32_e32 v2, v2, v3
	ds_bpermute_b32 v3, v37, v2
	s_waitcnt lgkmcnt(0)
	v_add_f32_e32 v2, v2, v3
	ds_bpermute_b32 v3, v38, v2
	s_waitcnt lgkmcnt(0)
	v_add_f32_e32 v2, v2, v3
	ds_bpermute_b32 v3, v39, v2
	s_waitcnt lgkmcnt(0)
	v_add_f32_e32 v2, v2, v3
	ds_bpermute_b32 v3, v40, v2
	s_and_saveexec_b64 s[16:17], s[38:39]
	s_cbranch_execz .LBB0_720
	s_waitcnt lgkmcnt(0)
	v_add_f32_e32 v2, v2, v3
	v_cndmask_b32_e64 v4, 0, v2, s[40:41]
	v_lshl_add_u64 v[2:3], s[12:13], 0, v[28:29]
	global_store_dword v[2:3], v4, off
	s_branch .LBB0_720

; #define GSYNC() do { for (int _r = 0; _r < SYNC_REPS; ++_r) xcd_barrier(xbar); } while (0)
; __device__ __forceinline__ PP get_pp() { PP q = (PP)__builtin_amdgcn_kernarg_segment_ptr(); asm volatile("" : "+s"(q)); return q; }
; __device__ __forceinline__ int bid_fresh() { int t = blockIdx.x; asm volatile("" : "+s"(t)); return t; }
; #define PG8_LAS __attribute__((address_space(3)))
; __global__ void __launch_bounds__(512, 2) hymba_fwd(Params p_unused) {
;     ...
;         { PP p = get_pp(); unsigned char* ws = p->ws;
;           pg8::SmallOrder S{(int)gridDim.x, (int)bid_fresh()};
;           pg8::Gemm g{(const bf16_t*)(ws + WS_GPH), (const bf16_t*)(ws + WS_WSM) + (size_t)l * 1536 * 512, T, 1536, 512, 512};
;           pg8::EpiSmall E{(bf16_t*)(ws + WS_YN), (const bf16_t*)(ws + WS_GPH), p->in[16] + (size_t)l * 512, (float*)(ws + WS_SSG)};
;           pg8::gemm_phase<pg8::EpiSmall, pg8::SmallOrder>((PG8_LAS unsigned char*)shm, g, S, E); }
;         GSYNC();
.Ltc_p4_idle:
	s_waitcnt lgkmcnt(0)
	v_readlane_b32 s2, v255, 20
	s_nop 3
	s_cmp_ge_u32 s2, 3
	s_cbranch_scc1 .Ltc_skipcall_2
	v_writelane_b32 v124, s2, 0
	v_writelane_b32 v124, s3, 1
	v_writelane_b32 v124, s4, 2
	v_writelane_b32 v124, s5, 3
	v_writelane_b32 v124, s6, 4
	v_writelane_b32 v124, s7, 5
	v_writelane_b32 v124, s12, 6
	v_writelane_b32 v124, s13, 7
	v_writelane_b32 v124, s14, 8
	v_writelane_b32 v124, s15, 9
	v_writelane_b32 v124, s27, 10
	v_writelane_b32 v124, s28, 11
	v_writelane_b32 v124, s29, 12
	v_writelane_b32 v124, s30, 13
	v_writelane_b32 v124, s31, 14
	v_writelane_b32 v124, s33, 15
	v_writelane_b32 v124, s34, 16
	v_writelane_b32 v124, s35, 17
	v_writelane_b32 v124, s36, 18
	v_writelane_b32 v124, s37, 19
	v_writelane_b32 v124, s38, 20
	v_writelane_b32 v124, s39, 21
	v_writelane_b32 v124, s40, 22
	v_writelane_b32 v124, s41, 23
	v_writelane_b32 v124, s42, 24
	v_writelane_b32 v124, s43, 25
	v_writelane_b32 v124, s44, 26
	v_writelane_b32 v124, s45, 27
	v_writelane_b32 v124, s46, 28
	v_writelane_b32 v124, s47, 29
	v_writelane_b32 v124, s48, 30
	v_writelane_b32 v124, s49, 31
	v_writelane_b32 v124, s50, 32
	v_writelane_b32 v124, s51, 33
	v_writelane_b32 v124, s52, 34
	v_writelane_b32 v124, s53, 35
	v_writelane_b32 v124, s54, 36
	v_writelane_b32 v124, s55, 37
	v_writelane_b32 v124, s56, 38
	v_writelane_b32 v124, s57, 39
	v_writelane_b32 v124, s58, 40
	v_writelane_b32 v124, s59, 41
	v_writelane_b32 v124, s60, 42
	v_writelane_b32 v124, s61, 43
	v_writelane_b32 v124, s62, 44
	v_writelane_b32 v124, s63, 45
	v_writelane_b32 v124, s64, 46
	v_writelane_b32 v124, s65, 47
	v_writelane_b32 v124, s68, 48
	v_writelane_b32 v124, s69, 49
	v_writelane_b32 v124, s70, 50
	v_writelane_b32 v124, s71, 51
	v_writelane_b32 v124, s72, 52
	v_writelane_b32 v124, s73, 53
	v_writelane_b32 v124, s74, 54
	v_writelane_b32 v124, s75, 55
	v_writelane_b32 v124, s76, 56
	v_writelane_b32 v124, s77, 57
	v_writelane_b32 v124, s78, 58
	v_writelane_b32 v124, s79, 59
	v_writelane_b32 v124, s80, 60
	v_writelane_b32 v124, s81, 61
	v_writelane_b32 v124, s82, 62
	v_writelane_b32 v124, s83, 63
	v_writelane_b32 v125, s84, 0
	v_writelane_b32 v125, s85, 1
	s_mov_b32 s84, 0x400
	s_mov_b32 s85, 0
	v_readlane_b32 s29, v254, 2
	v_readlane_b32 s27, v255, 20
	s_mov_b64 s[14:15], s[0:1]
	s_load_dwordx2 s[12:13], s[0:1], 0x110
	s_nop 3
	s_sub_u32 s29, s29, 192
	s_mov_b32 s63, 64
	s_mov_b32 s64, s27
	s_add_u32 s65, s27, 2
	s_min_u32 s65, s65, 4
	s_add_u32 s27, s27, 1
	s_mov_b32 s28, 0
	v_writelane_b32 v255, 2, 62
	s_branch .Ltc_entry
